# 64-byte alignment (p2alignl, s_nop fill) of the GEMM K-loop heads, RWKV scan loop and helper loop heads
# speedup vs baseline: 1.0220x; 1.0040x over previous
; template <class Epi>
; DEVI void gemm_phase(LAS unsigned char* lds, const Gemm g, const StaticOrder& S_, const Epi& E) {
;     ...
;     for (;;) {
;         const bool has_next = S_.next(ui + 1, nxt);
;         const char* nA = has_next ? (const char*)g.A + (size_t)nxt.pm * tstep : cA; const char* nB = has_next ? (const char*)g.Bt + (size_t)nxt.pn * tstep : cB;
;         for (int t = 0; t < nt; t += 2) {
;             const bool last = (t == nt - 2);
;             const char* a1 = cA + (size_t)(t + 1) * kstep;
;             const char* a2 = last ? nA : cA + (size_t)(t + 2) * kstep; const char* b2 = last ? nB : cB + (size_t)(t + 2) * kstep;
;     ...
; #pragma unroll
;         for (int a = 0; a < 2; ++a)
; #pragma unroll
;             for (int b = 0; b < 2; ++b)
; #pragma unroll
;                 for (int m = 0; m < 4; ++m)
; #pragma unroll
;                     for (int n = 0; n < 2; ++n) acc[a][b][m][n] = (f32x4){0.f, 0.f, 0.f, 0.f};
;         cur = nxt; cA = nA; cB = nB; ++ui;
.LBB0_215:
	v_mov_b32_e32 v123, 0
	s_andn2_b64 vcc, exec, s[16:17]
	v_mov_b32_e32 v122, v123
	v_mov_b32_e32 v121, v123
	v_mov_b32_e32 v120, v123
	v_mov_b32_e32 v127, v123
	v_mov_b32_e32 v126, v123
	v_mov_b32_e32 v125, v123
	v_mov_b32_e32 v124, v123
	v_mov_b32_e32 v111, v123
	v_mov_b32_e32 v110, v123
	v_mov_b32_e32 v109, v123
	v_mov_b32_e32 v108, v123
	v_mov_b32_e32 v107, v123
	v_mov_b32_e32 v106, v123
	v_mov_b32_e32 v105, v123
	v_mov_b32_e32 v104, v123
	v_mov_b32_e32 v95, v123
	v_mov_b32_e32 v94, v123
	v_mov_b32_e32 v93, v123
	v_mov_b32_e32 v92, v123
	v_mov_b32_e32 v91, v123
	v_mov_b32_e32 v90, v123
	v_mov_b32_e32 v89, v123
	v_mov_b32_e32 v88, v123
	v_mov_b32_e32 v79, v123
	v_mov_b32_e32 v78, v123
	v_mov_b32_e32 v77, v123
	v_mov_b32_e32 v76, v123
	v_mov_b32_e32 v75, v123
	v_mov_b32_e32 v74, v123
	v_mov_b32_e32 v73, v123
	v_mov_b32_e32 v72, v123
	v_mov_b32_e32 v119, v123
	v_mov_b32_e32 v118, v123
	v_mov_b32_e32 v117, v123
	v_mov_b32_e32 v116, v123
	v_mov_b32_e32 v115, v123
	v_mov_b32_e32 v114, v123
	v_mov_b32_e32 v113, v123
	v_mov_b32_e32 v112, v123
	v_mov_b32_e32 v103, v123
	v_mov_b32_e32 v102, v123
	v_mov_b32_e32 v101, v123
	v_mov_b32_e32 v100, v123
	v_mov_b32_e32 v99, v123
	v_mov_b32_e32 v98, v123
	v_mov_b32_e32 v97, v123
	v_mov_b32_e32 v96, v123
	v_mov_b32_e32 v87, v123
	v_mov_b32_e32 v86, v123
	v_mov_b32_e32 v85, v123
	v_mov_b32_e32 v84, v123
	v_mov_b32_e32 v83, v123
	v_mov_b32_e32 v82, v123
	v_mov_b32_e32 v81, v123
	v_mov_b32_e32 v80, v123
	v_mov_b32_e32 v71, v123
	v_mov_b32_e32 v70, v123
	v_mov_b32_e32 v69, v123
	v_mov_b32_e32 v68, v123
	v_mov_b32_e32 v67, v123
	v_mov_b32_e32 v66, v123
	v_mov_b32_e32 v65, v123
	v_mov_b32_e32 v64, v123
	v_mov_b32_e32 v63, v123
	v_mov_b32_e32 v62, v123
	v_mov_b32_e32 v61, v123
	v_mov_b32_e32 v60, v123
	v_mov_b32_e32 v59, v123
	v_mov_b32_e32 v58, v123
	v_mov_b32_e32 v57, v123
	v_mov_b32_e32 v56, v123
	v_mov_b32_e32 v47, v123
	v_mov_b32_e32 v46, v123
	v_mov_b32_e32 v45, v123
	v_mov_b32_e32 v44, v123
	v_mov_b32_e32 v43, v123
	v_mov_b32_e32 v42, v123
	v_mov_b32_e32 v41, v123
	v_mov_b32_e32 v40, v123
	v_mov_b32_e32 v31, v123
	v_mov_b32_e32 v30, v123
	v_mov_b32_e32 v29, v123
	v_mov_b32_e32 v28, v123
	v_mov_b32_e32 v27, v123
	v_mov_b32_e32 v26, v123
	v_mov_b32_e32 v25, v123
	v_mov_b32_e32 v24, v123
	v_mov_b32_e32 v15, v123
	v_mov_b32_e32 v14, v123
	v_mov_b32_e32 v13, v123
	v_mov_b32_e32 v12, v123
	v_mov_b32_e32 v11, v123
	v_mov_b32_e32 v10, v123
	v_mov_b32_e32 v9, v123
	v_mov_b32_e32 v8, v123
	v_mov_b32_e32 v55, v123
	v_mov_b32_e32 v54, v123
	v_mov_b32_e32 v53, v123
	v_mov_b32_e32 v52, v123
	v_mov_b32_e32 v51, v123
	v_mov_b32_e32 v50, v123
	v_mov_b32_e32 v49, v123
	v_mov_b32_e32 v48, v123
	v_mov_b32_e32 v39, v123
	v_mov_b32_e32 v38, v123
	v_mov_b32_e32 v37, v123
	v_mov_b32_e32 v36, v123
	v_mov_b32_e32 v35, v123
	v_mov_b32_e32 v34, v123
	v_mov_b32_e32 v33, v123
	v_mov_b32_e32 v32, v123
	v_mov_b32_e32 v23, v123
	v_mov_b32_e32 v22, v123
	v_mov_b32_e32 v21, v123
	v_mov_b32_e32 v20, v123
	v_mov_b32_e32 v19, v123
	v_mov_b32_e32 v18, v123
	v_mov_b32_e32 v17, v123
	v_mov_b32_e32 v16, v123
	v_mov_b32_e32 v7, v123
	v_mov_b32_e32 v6, v123
	v_mov_b32_e32 v5, v123
	v_mov_b32_e32 v4, v123
	v_mov_b32_e32 v3, v123
	v_mov_b32_e32 v2, v123
	v_mov_b32_e32 v1, v123
	v_mov_b32_e32 v0, v123
	s_cbranch_vccnz .LBB0_218
	s_add_u32 s8, s24, 0x80
	s_addc_u32 s9, s25, 0
	s_add_u32 s2, s22, 0x100
	v_mov_b32_e32 v0, 0
	s_addc_u32 s3, s23, 0
	s_mov_b32 s0, 0
	v_mov_b32_e32 v1, v0
	v_mov_b32_e32 v2, v0
	v_mov_b32_e32 v3, v0
	v_mov_b32_e32 v4, v0
	v_mov_b32_e32 v5, v0
	v_mov_b32_e32 v6, v0
	v_mov_b32_e32 v7, v0
	v_mov_b32_e32 v16, v0
	v_mov_b32_e32 v17, v0
	v_mov_b32_e32 v18, v0
	v_mov_b32_e32 v19, v0
	v_mov_b32_e32 v20, v0
	v_mov_b32_e32 v21, v0
	v_mov_b32_e32 v22, v0
	v_mov_b32_e32 v23, v0
	v_mov_b32_e32 v32, v0
	v_mov_b32_e32 v33, v0
	v_mov_b32_e32 v34, v0
	v_mov_b32_e32 v35, v0
	v_mov_b32_e32 v36, v0
	v_mov_b32_e32 v37, v0
	v_mov_b32_e32 v38, v0
	v_mov_b32_e32 v39, v0
	v_mov_b32_e32 v48, v0
	v_mov_b32_e32 v49, v0
	v_mov_b32_e32 v50, v0
	v_mov_b32_e32 v51, v0
	v_mov_b32_e32 v52, v0
	v_mov_b32_e32 v53, v0
	v_mov_b32_e32 v54, v0
	v_mov_b32_e32 v55, v0
	v_mov_b32_e32 v8, v0
	v_mov_b32_e32 v9, v0
	v_mov_b32_e32 v10, v0
	v_mov_b32_e32 v11, v0
	v_mov_b32_e32 v12, v0
	v_mov_b32_e32 v13, v0
	v_mov_b32_e32 v14, v0
	v_mov_b32_e32 v15, v0
	v_mov_b32_e32 v24, v0
	v_mov_b32_e32 v25, v0
	v_mov_b32_e32 v26, v0
	v_mov_b32_e32 v27, v0
	v_mov_b32_e32 v28, v0
	v_mov_b32_e32 v29, v0
	v_mov_b32_e32 v30, v0
	v_mov_b32_e32 v31, v0
	v_mov_b32_e32 v40, v0
	v_mov_b32_e32 v41, v0
	v_mov_b32_e32 v42, v0
	v_mov_b32_e32 v43, v0
	v_mov_b32_e32 v44, v0
	v_mov_b32_e32 v45, v0
	v_mov_b32_e32 v46, v0
	v_mov_b32_e32 v47, v0
	v_mov_b32_e32 v56, v0
	v_mov_b32_e32 v57, v0
	v_mov_b32_e32 v58, v0
	v_mov_b32_e32 v59, v0
	v_mov_b32_e32 v60, v0
	v_mov_b32_e32 v61, v0
	v_mov_b32_e32 v62, v0
	v_mov_b32_e32 v63, v0
	v_mov_b32_e32 v64, v0
	v_mov_b32_e32 v65, v0
	v_mov_b32_e32 v66, v0
	v_mov_b32_e32 v67, v0
	v_mov_b32_e32 v68, v0
	v_mov_b32_e32 v69, v0
	v_mov_b32_e32 v70, v0
	v_mov_b32_e32 v71, v0
	v_mov_b32_e32 v80, v0
	v_mov_b32_e32 v81, v0
	v_mov_b32_e32 v82, v0
	v_mov_b32_e32 v83, v0
	v_mov_b32_e32 v84, v0
	v_mov_b32_e32 v85, v0
	v_mov_b32_e32 v86, v0
	v_mov_b32_e32 v87, v0
	v_mov_b32_e32 v96, v0
	v_mov_b32_e32 v97, v0
	v_mov_b32_e32 v98, v0
	v_mov_b32_e32 v99, v0
	v_mov_b32_e32 v100, v0
	v_mov_b32_e32 v101, v0
	v_mov_b32_e32 v102, v0
	v_mov_b32_e32 v103, v0
	v_mov_b32_e32 v112, v0
	v_mov_b32_e32 v113, v0
	v_mov_b32_e32 v114, v0
	v_mov_b32_e32 v115, v0
	v_mov_b32_e32 v116, v0
	v_mov_b32_e32 v117, v0
	v_mov_b32_e32 v118, v0
	v_mov_b32_e32 v119, v0
	v_mov_b32_e32 v72, v0
	v_mov_b32_e32 v73, v0
	v_mov_b32_e32 v74, v0
	v_mov_b32_e32 v75, v0
	v_mov_b32_e32 v76, v0
	v_mov_b32_e32 v77, v0
	v_mov_b32_e32 v78, v0
	v_mov_b32_e32 v79, v0
	v_mov_b32_e32 v88, v0
	v_mov_b32_e32 v89, v0
	v_mov_b32_e32 v90, v0
	v_mov_b32_e32 v91, v0
	v_mov_b32_e32 v92, v0
	v_mov_b32_e32 v93, v0
	v_mov_b32_e32 v94, v0
	v_mov_b32_e32 v95, v0
	v_mov_b32_e32 v104, v0
	v_mov_b32_e32 v105, v0
	v_mov_b32_e32 v106, v0
	v_mov_b32_e32 v107, v0
	v_mov_b32_e32 v108, v0
	v_mov_b32_e32 v109, v0
	v_mov_b32_e32 v110, v0
	v_mov_b32_e32 v111, v0
	v_mov_b32_e32 v124, v0
	v_mov_b32_e32 v125, v0
	v_mov_b32_e32 v126, v0
	v_mov_b32_e32 v127, v0
	v_mov_b32_e32 v120, v0
	v_mov_b32_e32 v121, v0
	v_mov_b32_e32 v122, v0
	v_mov_b32_e32 v123, v0
	.p2alignl 6, 3212836864

; #define RW_HELP(u, PNEXT, PCUR) { const int c = c0 + (u); if (c + 1 < NCH) commit((c + 1) & 1, PNEXT); if (c + 4 < NCH) issue(c + 4, PCUR); if (c > 0) reduce_store(c - 1); RAW_BAR; }
; DEVI void rwkv_scan(const Params& p, unsigned char* smem, int b) {
;     ...
;     const int row = quarter * 16 + role * 4 + (lane >> 4), cgp = (lane & 15) * 4;
;     f32x2 s01 = {0.f, 0.f}, s23 = {0.f, 0.f};
;     if (helper) {
;         for (int c0 = 0; c0 < NCH; c0 += 4) {
;     ...
;             RW_HELP(0, pr1, pr0) RW_HELP(1, pr2, pr1) RW_HELP(2, pr3, pr2) RW_HELP(3, pr0, pr3)
;     ...
;         }
;     } else for (int chunk = 0; chunk < NCH; ++chunk) {
;         {
;             const float* bb = stg + (chunk & 1) * BUF;
;             float* pw = part + (chunk & 1) * (CH * 256) + role * 64 + lane;
;             f32x4 A1, A2, R1, WW, BW, KW, B2, K2, R2, SC; f32x2 VV;
;             f32x4 A1n, A2n, R1n, WWn, BWn, KWn, B2n, K2n, R2n, SCn; f32x2 VVn;
;             {
;                 const float* vp = bb + cgp;
;                 A1n = *(const f32x4*)(vp); A2n = *(const f32x4*)(vp + 64); R1n = *(const f32x4*)(vp + 128); WWn = *(const f32x4*)(vp + 192); BWn = *(const f32x4*)(vp + 256);
;                 KWn = *(const f32x4*)(vp + 320); B2n = *(const f32x4*)(vp + 384); K2n = *(const f32x4*)(vp + 448); R2n = *(const f32x4*)(vp + 512);
;                 SCn = *(const f32x4*)(bb + VEC); VVn = *(const f32x2*)(bb + VEC + SCL + row * 2);
;             }
; #pragma unroll
;             for (int rd = 0; rd < NR; ++rd) {
.LBB0_686:
	s_add_u32 s12, s30, 0x33f00000
	s_addc_u32 s13, s31, 0
	s_mov_b64 s[0:1], -1
	s_andn2_b64 vcc, exec, s[14:15]
	v_lshlrev_b32_e32 v120, 2, v112
	s_waitcnt lgkmcnt(0)
	s_barrier
	s_cbranch_vccnz .LBB0_690
	s_lshl_b32 s0, s2, 2
	v_readlane_b32 s1, v254, 42
	s_add_i32 s0, s0, s1
	v_lshrrev_b32_e32 v32, 4, v110
	v_or_b32_e32 v32, s0, v32
	s_lshl_b32 s0, s3, 2
	s_add_i32 s0, s0, 0
	s_waitcnt vmcnt(18)
	v_lshlrev_b32_e32 v92, 3, v32
	v_mov_b32_e32 v32, 0
	v_and_b32_e32 v89, 60, v120
	v_lshl_add_u32 v91, v110, 2, s0
	s_mov_b32 s0, 0
	v_mov_b32_e32 v33, v32
	v_mov_b32_e32 v36, v32
	v_mov_b32_e32 v37, v32
	.p2alignl 6, 3212836864

; #define RW_HELP(u, PNEXT, PCUR) { const int c = c0 + (u); if (c + 1 < NCH) commit((c + 1) & 1, PNEXT); if (c + 4 < NCH) issue(c + 4, PCUR); if (c > 0) reduce_store(c - 1); RAW_BAR; }
; DEVI void rwkv_scan(const Params& p, unsigned char* smem, int b) {
;     ...
;     auto reduce_store = [&](int chunk) {
;         const int t = lt >> 4, k = (lt >> 2) & 3, rr = lt & 3;
;         const f32x4* pp = (const f32x4*)(part + ((chunk & 1) * CH + t) * 256 + k * 64 + rr * 16);
;         const f32x4 s4 = pp[0] + pp[1] + pp[2] + pp[3];
;         Y[(size_t)(chunk * CH + t) * 512 + head * 64 + quarter * 16 + k * 4 + rr] = (s4[0] + s4[1]) + (s4[2] + s4[3]);
;     };
;     Pre pr0, pr1, pr2, pr3;
;     if (helper) { issue(0, pr0); commit(0, pr0); issue(1, pr1); issue(2, pr2); issue(3, pr3); }
;     __syncthreads();
;     const int row = quarter * 16 + role * 4 + (lane >> 4), cgp = (lane & 15) * 4;
;     f32x2 s01 = {0.f, 0.f}, s23 = {0.f, 0.f};
;     if (helper) {
;         for (int c0 = 0; c0 < NCH; c0 += 4) {
;     ...
;             RW_HELP(0, pr1, pr0) RW_HELP(1, pr2, pr1) RW_HELP(2, pr3, pr2) RW_HELP(3, pr0, pr3)
.LBB0_733:
	ds_read_b128 v[32:35], v119 offset:45312
	ds_read_b128 v[36:39], v119 offset:45328
	ds_read_b128 v[120:123], v119 offset:45344
	ds_read_b128 v[124:127], v119 offset:45360
	s_mov_b64 s[0:1], 0x10000
	v_lshl_add_u64 v[104:105], v[104:105], 0, s[0:1]
	s_waitcnt lgkmcnt(2)
	v_pk_add_f32 v[34:35], v[34:35], v[38:39]
	v_pk_add_f32 v[32:33], v[32:33], v[36:37]
	s_waitcnt lgkmcnt(1)
	v_pk_add_f32 v[34:35], v[34:35], v[122:123]
	v_pk_add_f32 v[32:33], v[32:33], v[120:121]
	s_waitcnt lgkmcnt(0)
	v_pk_add_f32 v[34:35], v[34:35], v[126:127]
	v_pk_add_f32 v[32:33], v[32:33], v[124:125]
	s_mov_b64 s[0:1], 0x20000
	v_pk_mov_b32 v[36:37], v[32:33], v[34:35] op_sel:[1,0]
	v_mov_b32_e32 v33, v35
	v_pk_add_f32 v[32:33], v[36:37], v[32:33]
	v_lshl_add_u64 v[106:107], v[106:107], 0, s[0:1]
	v_add_f32_e32 v34, v32, v33
	v_add_co_u32_e32 v32, vcc, 0x33f30000, v110
	v_lshl_add_u64 v[108:109], v[108:109], 0, s[0:1]
	s_nop 0
	v_addc_co_u32_e32 v33, vcc, 0, v111, vcc
	global_store_dword v[32:33], v34, off
	s_waitcnt lgkmcnt(0)
	s_barrier
	s_and_b64 vcc, exec, s[14:15]
	s_cbranch_vccnz .LBB0_783
	.p2alignl 6, 3212836864

; template <class Epi>
; DEVI void gemm_phase(LAS unsigned char* lds, const Gemm g, const StaticOrder& S_, const Epi& E) {
;     ...
;     for (;;) {
;         const bool has_next = S_.next(ui + 1, nxt);
;         const char* nA = has_next ? (const char*)g.A + (size_t)nxt.pm * tstep : cA; const char* nB = has_next ? (const char*)g.Bt + (size_t)nxt.pn * tstep : cB;
;         for (int t = 0; t < nt; t += 2) {
;             const bool last = (t == nt - 2);
;             const char* a1 = cA + (size_t)(t + 1) * kstep;
;             const char* a2 = last ? nA : cA + (size_t)(t + 2) * kstep; const char* b2 = last ? nB : cB + (size_t)(t + 2) * kstep;
;     ...
; #pragma unroll
;         for (int a = 0; a < 2; ++a)
; #pragma unroll
;             for (int b = 0; b < 2; ++b)
; #pragma unroll
;                 for (int m = 0; m < 4; ++m)
; #pragma unroll
;                     for (int n = 0; n < 2; ++n) acc[a][b][m][n] = (f32x4){0.f, 0.f, 0.f, 0.f};
;         cur = nxt; cA = nA; cB = nB; ++ui;
.LBB0_824:
	v_mov_b32_e32 v127, 0
	s_andn2_b64 vcc, exec, s[18:19]
	v_mov_b32_e32 v126, v127
	v_mov_b32_e32 v125, v127
	v_mov_b32_e32 v124, v127
	v_mov_b32_e32 v123, v127
	v_mov_b32_e32 v122, v127
	v_mov_b32_e32 v121, v127
	v_mov_b32_e32 v120, v127
	v_mov_b32_e32 v111, v127
	v_mov_b32_e32 v110, v127
	v_mov_b32_e32 v109, v127
	v_mov_b32_e32 v108, v127
	v_mov_b32_e32 v107, v127
	v_mov_b32_e32 v106, v127
	v_mov_b32_e32 v105, v127
	v_mov_b32_e32 v104, v127
	s_waitcnt vmcnt(0)
	v_mov_b32_e32 v95, v127
	v_mov_b32_e32 v94, v127
	v_mov_b32_e32 v93, v127
	v_mov_b32_e32 v92, v127
	v_mov_b32_e32 v91, v127
	v_mov_b32_e32 v90, v127
	v_mov_b32_e32 v89, v127
	v_mov_b32_e32 v88, v127
	v_mov_b32_e32 v79, v127
	v_mov_b32_e32 v78, v127
	v_mov_b32_e32 v77, v127
	v_mov_b32_e32 v76, v127
	v_mov_b32_e32 v75, v127
	v_mov_b32_e32 v74, v127
	v_mov_b32_e32 v73, v127
	v_mov_b32_e32 v72, v127
	v_mov_b32_e32 v119, v127
	v_mov_b32_e32 v118, v127
	v_mov_b32_e32 v117, v127
	v_mov_b32_e32 v116, v127
	v_mov_b32_e32 v115, v127
	v_mov_b32_e32 v114, v127
	v_mov_b32_e32 v113, v127
	v_mov_b32_e32 v112, v127
	v_mov_b32_e32 v103, v127
	v_mov_b32_e32 v102, v127
	v_mov_b32_e32 v101, v127
	v_mov_b32_e32 v100, v127
	v_mov_b32_e32 v99, v127
	v_mov_b32_e32 v98, v127
	v_mov_b32_e32 v97, v127
	v_mov_b32_e32 v96, v127
	v_mov_b32_e32 v87, v127
	v_mov_b32_e32 v86, v127
	v_mov_b32_e32 v85, v127
	v_mov_b32_e32 v84, v127
	v_mov_b32_e32 v83, v127
	v_mov_b32_e32 v82, v127
	v_mov_b32_e32 v81, v127
	v_mov_b32_e32 v80, v127
	v_mov_b32_e32 v71, v127
	v_mov_b32_e32 v70, v127
	v_mov_b32_e32 v69, v127
	v_mov_b32_e32 v68, v127
	v_mov_b32_e32 v67, v127
	v_mov_b32_e32 v66, v127
	v_mov_b32_e32 v65, v127
	v_mov_b32_e32 v64, v127
	v_mov_b32_e32 v63, v127
	v_mov_b32_e32 v62, v127
	v_mov_b32_e32 v61, v127
	v_mov_b32_e32 v60, v127
	v_mov_b32_e32 v59, v127
	v_mov_b32_e32 v58, v127
	v_mov_b32_e32 v57, v127
	v_mov_b32_e32 v56, v127
	v_mov_b32_e32 v47, v127
	v_mov_b32_e32 v46, v127
	v_mov_b32_e32 v45, v127
	v_mov_b32_e32 v44, v127
	v_mov_b32_e32 v43, v127
	v_mov_b32_e32 v42, v127
	v_mov_b32_e32 v41, v127
	v_mov_b32_e32 v40, v127
	v_mov_b32_e32 v31, v127
	v_mov_b32_e32 v30, v127
	v_mov_b32_e32 v29, v127
	v_mov_b32_e32 v28, v127
	v_mov_b32_e32 v27, v127
	v_mov_b32_e32 v26, v127
	v_mov_b32_e32 v25, v127
	v_mov_b32_e32 v24, v127
	v_mov_b32_e32 v15, v127
	v_mov_b32_e32 v14, v127
	v_mov_b32_e32 v13, v127
	v_mov_b32_e32 v12, v127
	v_mov_b32_e32 v11, v127
	v_mov_b32_e32 v10, v127
	v_mov_b32_e32 v9, v127
	v_mov_b32_e32 v8, v127
	v_mov_b32_e32 v55, v127
	v_mov_b32_e32 v54, v127
	v_mov_b32_e32 v53, v127
	v_mov_b32_e32 v52, v127
	v_mov_b32_e32 v51, v127
	v_mov_b32_e32 v50, v127
	v_mov_b32_e32 v49, v127
	v_mov_b32_e32 v48, v127
	v_mov_b32_e32 v39, v127
	v_mov_b32_e32 v38, v127
	v_mov_b32_e32 v37, v127
	v_mov_b32_e32 v36, v127
	v_mov_b32_e32 v35, v127
	v_mov_b32_e32 v34, v127
	v_mov_b32_e32 v33, v127
	v_mov_b32_e32 v32, v127
	v_mov_b32_e32 v23, v127
	v_mov_b32_e32 v22, v127
	v_mov_b32_e32 v21, v127
	v_mov_b32_e32 v20, v127
	v_mov_b32_e32 v19, v127
	v_mov_b32_e32 v18, v127
	v_mov_b32_e32 v17, v127
	v_mov_b32_e32 v16, v127
	v_mov_b32_e32 v7, v127
	v_mov_b32_e32 v6, v127
	v_mov_b32_e32 v5, v127
	v_mov_b32_e32 v4, v127
	v_mov_b32_e32 v3, v127
	v_mov_b32_e32 v2, v127
	v_mov_b32_e32 v1, v127
	v_mov_b32_e32 v0, v127
	s_cbranch_vccnz .LBB0_813
	s_add_u32 s20, s20, 0x80
	s_addc_u32 s21, s21, 0
	s_add_u32 s2, s22, 0x100
	v_mov_b32_e32 v0, 0
	s_addc_u32 s3, s23, 0
	s_mov_b32 s0, 0
	v_mov_b32_e32 v1, v0
	v_mov_b32_e32 v2, v0
	v_mov_b32_e32 v3, v0
	v_mov_b32_e32 v4, v0
	v_mov_b32_e32 v5, v0
	v_mov_b32_e32 v6, v0
	v_mov_b32_e32 v7, v0
	v_mov_b32_e32 v16, v0
	v_mov_b32_e32 v17, v0
	v_mov_b32_e32 v18, v0
	v_mov_b32_e32 v19, v0
	v_mov_b32_e32 v20, v0
	v_mov_b32_e32 v21, v0
	v_mov_b32_e32 v22, v0
	v_mov_b32_e32 v23, v0
	v_mov_b32_e32 v32, v0
	v_mov_b32_e32 v33, v0
	v_mov_b32_e32 v34, v0
	v_mov_b32_e32 v35, v0
	v_mov_b32_e32 v36, v0
	v_mov_b32_e32 v37, v0
	v_mov_b32_e32 v38, v0
	v_mov_b32_e32 v39, v0
	v_mov_b32_e32 v48, v0
	v_mov_b32_e32 v49, v0
	v_mov_b32_e32 v50, v0
	v_mov_b32_e32 v51, v0
	v_mov_b32_e32 v52, v0
	v_mov_b32_e32 v53, v0
	v_mov_b32_e32 v54, v0
	v_mov_b32_e32 v55, v0
	v_mov_b32_e32 v8, v0
	v_mov_b32_e32 v9, v0
	v_mov_b32_e32 v10, v0
	v_mov_b32_e32 v11, v0
	v_mov_b32_e32 v12, v0
	v_mov_b32_e32 v13, v0
	v_mov_b32_e32 v14, v0
	v_mov_b32_e32 v15, v0
	v_mov_b32_e32 v24, v0
	v_mov_b32_e32 v25, v0
	v_mov_b32_e32 v26, v0
	v_mov_b32_e32 v27, v0
	v_mov_b32_e32 v28, v0
	v_mov_b32_e32 v29, v0
	v_mov_b32_e32 v30, v0
	v_mov_b32_e32 v31, v0
	v_mov_b32_e32 v40, v0
	v_mov_b32_e32 v41, v0
	v_mov_b32_e32 v42, v0
	v_mov_b32_e32 v43, v0
	v_mov_b32_e32 v44, v0
	v_mov_b32_e32 v45, v0
	v_mov_b32_e32 v46, v0
	v_mov_b32_e32 v47, v0
	v_mov_b32_e32 v56, v0
	v_mov_b32_e32 v57, v0
	v_mov_b32_e32 v58, v0
	v_mov_b32_e32 v59, v0
	v_mov_b32_e32 v60, v0
	v_mov_b32_e32 v61, v0
	v_mov_b32_e32 v62, v0
	v_mov_b32_e32 v63, v0
	v_mov_b32_e32 v64, v0
	v_mov_b32_e32 v65, v0
	v_mov_b32_e32 v66, v0
	v_mov_b32_e32 v67, v0
	v_mov_b32_e32 v68, v0
	v_mov_b32_e32 v69, v0
	v_mov_b32_e32 v70, v0
	v_mov_b32_e32 v71, v0
	v_mov_b32_e32 v80, v0
	v_mov_b32_e32 v81, v0
	v_mov_b32_e32 v82, v0
	v_mov_b32_e32 v83, v0
	v_mov_b32_e32 v84, v0
	v_mov_b32_e32 v85, v0
	v_mov_b32_e32 v86, v0
	v_mov_b32_e32 v87, v0
	v_mov_b32_e32 v96, v0
	v_mov_b32_e32 v97, v0
	v_mov_b32_e32 v98, v0
	v_mov_b32_e32 v99, v0
	v_mov_b32_e32 v100, v0
	v_mov_b32_e32 v101, v0
	v_mov_b32_e32 v102, v0
	v_mov_b32_e32 v103, v0
	v_mov_b32_e32 v112, v0
	v_mov_b32_e32 v113, v0
	v_mov_b32_e32 v114, v0
	v_mov_b32_e32 v115, v0
	v_mov_b32_e32 v116, v0
	v_mov_b32_e32 v117, v0
	v_mov_b32_e32 v118, v0
	v_mov_b32_e32 v119, v0
	v_mov_b32_e32 v72, v0
	v_mov_b32_e32 v73, v0
	v_mov_b32_e32 v74, v0
	v_mov_b32_e32 v75, v0
	v_mov_b32_e32 v76, v0
	v_mov_b32_e32 v77, v0
	v_mov_b32_e32 v78, v0
	v_mov_b32_e32 v79, v0
	v_mov_b32_e32 v88, v0
	v_mov_b32_e32 v89, v0
	v_mov_b32_e32 v90, v0
	v_mov_b32_e32 v91, v0
	v_mov_b32_e32 v92, v0
	v_mov_b32_e32 v93, v0
	v_mov_b32_e32 v94, v0
	v_mov_b32_e32 v95, v0
	v_mov_b32_e32 v104, v0
	v_mov_b32_e32 v105, v0
	v_mov_b32_e32 v106, v0
	v_mov_b32_e32 v107, v0
	v_mov_b32_e32 v108, v0
	v_mov_b32_e32 v109, v0
	v_mov_b32_e32 v110, v0
	v_mov_b32_e32 v111, v0
	v_mov_b32_e32 v120, v0
	v_mov_b32_e32 v121, v0
	v_mov_b32_e32 v122, v0
	v_mov_b32_e32 v123, v0
	v_mov_b32_e32 v124, v0
	v_mov_b32_e32 v125, v0
	v_mov_b32_e32 v126, v0
	v_mov_b32_e32 v127, v0
	.p2alignl 6, 3212836864

; template <class Epi>
; DEVI void gemm_phase(LAS unsigned char* lds, const Gemm g, const StaticOrder& S_, const Epi& E) {
;     ...
;     for (;;) {
;         const bool has_next = S_.next(ui + 1, nxt);
;         const char* nA = has_next ? (const char*)g.A + (size_t)nxt.pm * tstep : cA; const char* nB = has_next ? (const char*)g.Bt + (size_t)nxt.pn * tstep : cB;
;         for (int t = 0; t < nt; t += 2) {
;             const bool last = (t == nt - 2);
;             const char* a1 = cA + (size_t)(t + 1) * kstep;
;             const char* a2 = last ? nA : cA + (size_t)(t + 2) * kstep; const char* b2 = last ? nB : cB + (size_t)(t + 2) * kstep;
;     ...
; #pragma unroll
;         for (int a = 0; a < 2; ++a)
; #pragma unroll
;             for (int b = 0; b < 2; ++b)
; #pragma unroll
;                 for (int m = 0; m < 4; ++m)
; #pragma unroll
;                     for (int n = 0; n < 2; ++n) acc[a][b][m][n] = (f32x4){0.f, 0.f, 0.f, 0.f};
;         cur = nxt; cA = nA; cB = nB; ++ui;
.LBB0_918:
	v_mov_b32_e32 v127, 0
	s_andn2_b64 vcc, exec, s[20:21]
	v_mov_b32_e32 v126, v127
	v_mov_b32_e32 v125, v127
	v_mov_b32_e32 v124, v127
	v_mov_b32_e32 v123, v127
	v_mov_b32_e32 v122, v127
	v_mov_b32_e32 v121, v127
	v_mov_b32_e32 v120, v127
	v_mov_b32_e32 v111, v127
	v_mov_b32_e32 v110, v127
	v_mov_b32_e32 v109, v127
	v_mov_b32_e32 v108, v127
	v_mov_b32_e32 v107, v127
	v_mov_b32_e32 v106, v127
	v_mov_b32_e32 v105, v127
	v_mov_b32_e32 v104, v127
	s_waitcnt vmcnt(0)
	v_mov_b32_e32 v95, v127
	v_mov_b32_e32 v94, v127
	v_mov_b32_e32 v93, v127
	v_mov_b32_e32 v92, v127
	v_mov_b32_e32 v91, v127
	v_mov_b32_e32 v90, v127
	v_mov_b32_e32 v89, v127
	v_mov_b32_e32 v88, v127
	v_mov_b32_e32 v79, v127
	v_mov_b32_e32 v78, v127
	v_mov_b32_e32 v77, v127
	v_mov_b32_e32 v76, v127
	v_mov_b32_e32 v75, v127
	v_mov_b32_e32 v74, v127
	v_mov_b32_e32 v73, v127
	v_mov_b32_e32 v72, v127
	v_mov_b32_e32 v119, v127
	v_mov_b32_e32 v118, v127
	v_mov_b32_e32 v117, v127
	v_mov_b32_e32 v116, v127
	v_mov_b32_e32 v115, v127
	v_mov_b32_e32 v114, v127
	v_mov_b32_e32 v113, v127
	v_mov_b32_e32 v112, v127
	v_mov_b32_e32 v103, v127
	v_mov_b32_e32 v102, v127
	v_mov_b32_e32 v101, v127
	v_mov_b32_e32 v100, v127
	v_mov_b32_e32 v99, v127
	v_mov_b32_e32 v98, v127
	v_mov_b32_e32 v97, v127
	v_mov_b32_e32 v96, v127
	v_mov_b32_e32 v87, v127
	v_mov_b32_e32 v86, v127
	v_mov_b32_e32 v85, v127
	v_mov_b32_e32 v84, v127
	v_mov_b32_e32 v83, v127
	v_mov_b32_e32 v82, v127
	v_mov_b32_e32 v81, v127
	v_mov_b32_e32 v80, v127
	v_mov_b32_e32 v71, v127
	v_mov_b32_e32 v70, v127
	v_mov_b32_e32 v69, v127
	v_mov_b32_e32 v68, v127
	v_mov_b32_e32 v67, v127
	v_mov_b32_e32 v66, v127
	v_mov_b32_e32 v65, v127
	v_mov_b32_e32 v64, v127
	v_mov_b32_e32 v63, v127
	v_mov_b32_e32 v62, v127
	v_mov_b32_e32 v61, v127
	v_mov_b32_e32 v60, v127
	v_mov_b32_e32 v59, v127
	v_mov_b32_e32 v58, v127
	v_mov_b32_e32 v57, v127
	v_mov_b32_e32 v56, v127
	v_mov_b32_e32 v47, v127
	v_mov_b32_e32 v46, v127
	v_mov_b32_e32 v45, v127
	v_mov_b32_e32 v44, v127
	v_mov_b32_e32 v43, v127
	v_mov_b32_e32 v42, v127
	v_mov_b32_e32 v41, v127
	v_mov_b32_e32 v40, v127
	v_mov_b32_e32 v31, v127
	v_mov_b32_e32 v30, v127
	v_mov_b32_e32 v29, v127
	v_mov_b32_e32 v28, v127
	v_mov_b32_e32 v27, v127
	v_mov_b32_e32 v26, v127
	v_mov_b32_e32 v25, v127
	v_mov_b32_e32 v24, v127
	v_mov_b32_e32 v15, v127
	v_mov_b32_e32 v14, v127
	v_mov_b32_e32 v13, v127
	v_mov_b32_e32 v12, v127
	v_mov_b32_e32 v11, v127
	v_mov_b32_e32 v10, v127
	v_mov_b32_e32 v9, v127
	v_mov_b32_e32 v8, v127
	v_mov_b32_e32 v55, v127
	v_mov_b32_e32 v54, v127
	v_mov_b32_e32 v53, v127
	v_mov_b32_e32 v52, v127
	v_mov_b32_e32 v51, v127
	v_mov_b32_e32 v50, v127
	v_mov_b32_e32 v49, v127
	v_mov_b32_e32 v48, v127
	v_mov_b32_e32 v39, v127
	v_mov_b32_e32 v38, v127
	v_mov_b32_e32 v37, v127
	v_mov_b32_e32 v36, v127
	v_mov_b32_e32 v35, v127
	v_mov_b32_e32 v34, v127
	v_mov_b32_e32 v33, v127
	v_mov_b32_e32 v32, v127
	v_mov_b32_e32 v23, v127
	v_mov_b32_e32 v22, v127
	v_mov_b32_e32 v21, v127
	v_mov_b32_e32 v20, v127
	v_mov_b32_e32 v19, v127
	v_mov_b32_e32 v18, v127
	v_mov_b32_e32 v17, v127
	v_mov_b32_e32 v16, v127
	v_mov_b32_e32 v7, v127
	v_mov_b32_e32 v6, v127
	v_mov_b32_e32 v5, v127
	v_mov_b32_e32 v4, v127
	v_mov_b32_e32 v3, v127
	v_mov_b32_e32 v2, v127
	v_mov_b32_e32 v1, v127
	v_mov_b32_e32 v0, v127
	s_cbranch_vccnz .LBB0_907
	s_add_u32 s22, s22, 0x80
	s_addc_u32 s23, s23, 0
	s_add_u32 s2, s24, 0x100
	v_mov_b32_e32 v0, 0
	s_addc_u32 s3, s25, 0
	s_mov_b32 s0, 0
	v_mov_b32_e32 v1, v0
	v_mov_b32_e32 v2, v0
	v_mov_b32_e32 v3, v0
	v_mov_b32_e32 v4, v0
	v_mov_b32_e32 v5, v0
	v_mov_b32_e32 v6, v0
	v_mov_b32_e32 v7, v0
	v_mov_b32_e32 v16, v0
	v_mov_b32_e32 v17, v0
	v_mov_b32_e32 v18, v0
	v_mov_b32_e32 v19, v0
	v_mov_b32_e32 v20, v0
	v_mov_b32_e32 v21, v0
	v_mov_b32_e32 v22, v0
	v_mov_b32_e32 v23, v0
	v_mov_b32_e32 v32, v0
	v_mov_b32_e32 v33, v0
	v_mov_b32_e32 v34, v0
	v_mov_b32_e32 v35, v0
	v_mov_b32_e32 v36, v0
	v_mov_b32_e32 v37, v0
	v_mov_b32_e32 v38, v0
	v_mov_b32_e32 v39, v0
	v_mov_b32_e32 v48, v0
	v_mov_b32_e32 v49, v0
	v_mov_b32_e32 v50, v0
	v_mov_b32_e32 v51, v0
	v_mov_b32_e32 v52, v0
	v_mov_b32_e32 v53, v0
	v_mov_b32_e32 v54, v0
	v_mov_b32_e32 v55, v0
	v_mov_b32_e32 v8, v0
	v_mov_b32_e32 v9, v0
	v_mov_b32_e32 v10, v0
	v_mov_b32_e32 v11, v0
	v_mov_b32_e32 v12, v0
	v_mov_b32_e32 v13, v0
	v_mov_b32_e32 v14, v0
	v_mov_b32_e32 v15, v0
	v_mov_b32_e32 v24, v0
	v_mov_b32_e32 v25, v0
	v_mov_b32_e32 v26, v0
	v_mov_b32_e32 v27, v0
	v_mov_b32_e32 v28, v0
	v_mov_b32_e32 v29, v0
	v_mov_b32_e32 v30, v0
	v_mov_b32_e32 v31, v0
	v_mov_b32_e32 v40, v0
	v_mov_b32_e32 v41, v0
	v_mov_b32_e32 v42, v0
	v_mov_b32_e32 v43, v0
	v_mov_b32_e32 v44, v0
	v_mov_b32_e32 v45, v0
	v_mov_b32_e32 v46, v0
	v_mov_b32_e32 v47, v0
	v_mov_b32_e32 v56, v0
	v_mov_b32_e32 v57, v0
	v_mov_b32_e32 v58, v0
	v_mov_b32_e32 v59, v0
	v_mov_b32_e32 v60, v0
	v_mov_b32_e32 v61, v0
	v_mov_b32_e32 v62, v0
	v_mov_b32_e32 v63, v0
	v_mov_b32_e32 v64, v0
	v_mov_b32_e32 v65, v0
	v_mov_b32_e32 v66, v0
	v_mov_b32_e32 v67, v0
	v_mov_b32_e32 v68, v0
	v_mov_b32_e32 v69, v0
	v_mov_b32_e32 v70, v0
	v_mov_b32_e32 v71, v0
	v_mov_b32_e32 v80, v0
	v_mov_b32_e32 v81, v0
	v_mov_b32_e32 v82, v0
	v_mov_b32_e32 v83, v0
	v_mov_b32_e32 v84, v0
	v_mov_b32_e32 v85, v0
	v_mov_b32_e32 v86, v0
	v_mov_b32_e32 v87, v0
	v_mov_b32_e32 v96, v0
	v_mov_b32_e32 v97, v0
	v_mov_b32_e32 v98, v0
	v_mov_b32_e32 v99, v0
	v_mov_b32_e32 v100, v0
	v_mov_b32_e32 v101, v0
	v_mov_b32_e32 v102, v0
	v_mov_b32_e32 v103, v0
	v_mov_b32_e32 v112, v0
	v_mov_b32_e32 v113, v0
	v_mov_b32_e32 v114, v0
	v_mov_b32_e32 v115, v0
	v_mov_b32_e32 v116, v0
	v_mov_b32_e32 v117, v0
	v_mov_b32_e32 v118, v0
	v_mov_b32_e32 v119, v0
	v_mov_b32_e32 v72, v0
	v_mov_b32_e32 v73, v0
	v_mov_b32_e32 v74, v0
	v_mov_b32_e32 v75, v0
	v_mov_b32_e32 v76, v0
	v_mov_b32_e32 v77, v0
	v_mov_b32_e32 v78, v0
	v_mov_b32_e32 v79, v0
	v_mov_b32_e32 v88, v0
	v_mov_b32_e32 v89, v0
	v_mov_b32_e32 v90, v0
	v_mov_b32_e32 v91, v0
	v_mov_b32_e32 v92, v0
	v_mov_b32_e32 v93, v0
	v_mov_b32_e32 v94, v0
	v_mov_b32_e32 v95, v0
	v_mov_b32_e32 v104, v0
	v_mov_b32_e32 v105, v0
	v_mov_b32_e32 v106, v0
	v_mov_b32_e32 v107, v0
	v_mov_b32_e32 v108, v0
	v_mov_b32_e32 v109, v0
	v_mov_b32_e32 v110, v0
	v_mov_b32_e32 v111, v0
	v_mov_b32_e32 v120, v0
	v_mov_b32_e32 v121, v0
	v_mov_b32_e32 v122, v0
	v_mov_b32_e32 v123, v0
	v_mov_b32_e32 v124, v0
	v_mov_b32_e32 v125, v0
	v_mov_b32_e32 v126, v0
	v_mov_b32_e32 v127, v0
	.p2alignl 6, 3212836864

; template <class Epi>
; DEVI void gemm_phase(LAS unsigned char* lds, const Gemm g, const StaticOrder& S_, const Epi& E) {
;     ...
;     for (;;) {
;         const bool has_next = S_.next(ui + 1, nxt);
;         const char* nA = has_next ? (const char*)g.A + (size_t)nxt.pm * tstep : cA; const char* nB = has_next ? (const char*)g.Bt + (size_t)nxt.pn * tstep : cB;
;         for (int t = 0; t < nt; t += 2) {
;             const bool last = (t == nt - 2);
;             const char* a1 = cA + (size_t)(t + 1) * kstep;
;             const char* a2 = last ? nA : cA + (size_t)(t + 2) * kstep; const char* b2 = last ? nB : cB + (size_t)(t + 2) * kstep;
;     ...
; #pragma unroll
;         for (int a = 0; a < 2; ++a)
; #pragma unroll
;             for (int b = 0; b < 2; ++b)
; #pragma unroll
;                 for (int m = 0; m < 4; ++m)
; #pragma unroll
;                     for (int n = 0; n < 2; ++n) acc[a][b][m][n] = (f32x4){0.f, 0.f, 0.f, 0.f};
;         cur = nxt; cA = nA; cB = nB; ++ui;
.LBB0_958:
	v_mov_b32_e32 v123, 0
	s_andn2_b64 vcc, exec, s[18:19]
	v_mov_b32_e32 v122, v123
	v_mov_b32_e32 v121, v123
	v_mov_b32_e32 v120, v123
	v_mov_b32_e32 v119, v123
	v_mov_b32_e32 v118, v123
	v_mov_b32_e32 v117, v123
	v_mov_b32_e32 v116, v123
	v_mov_b32_e32 v111, v123
	v_mov_b32_e32 v110, v123
	v_mov_b32_e32 v109, v123
	v_mov_b32_e32 v108, v123
	v_mov_b32_e32 v103, v123
	v_mov_b32_e32 v102, v123
	v_mov_b32_e32 v101, v123
	v_mov_b32_e32 v100, v123
	v_mov_b32_e32 v95, v123
	v_mov_b32_e32 v94, v123
	v_mov_b32_e32 v93, v123
	v_mov_b32_e32 v92, v123
	v_mov_b32_e32 v87, v123
	v_mov_b32_e32 v86, v123
	v_mov_b32_e32 v85, v123
	v_mov_b32_e32 v84, v123
	v_mov_b32_e32 v79, v123
	v_mov_b32_e32 v78, v123
	v_mov_b32_e32 v77, v123
	v_mov_b32_e32 v76, v123
	v_mov_b32_e32 v71, v123
	v_mov_b32_e32 v70, v123
	v_mov_b32_e32 v69, v123
	v_mov_b32_e32 v68, v123
	v_mov_b32_e32 v127, v123
	v_mov_b32_e32 v126, v123
	v_mov_b32_e32 v125, v123
	v_mov_b32_e32 v124, v123
	v_mov_b32_e32 v115, v123
	v_mov_b32_e32 v114, v123
	v_mov_b32_e32 v113, v123
	v_mov_b32_e32 v112, v123
	v_mov_b32_e32 v107, v123
	v_mov_b32_e32 v106, v123
	v_mov_b32_e32 v105, v123
	v_mov_b32_e32 v104, v123
	v_mov_b32_e32 v99, v123
	v_mov_b32_e32 v98, v123
	v_mov_b32_e32 v97, v123
	v_mov_b32_e32 v96, v123
	v_mov_b32_e32 v91, v123
	v_mov_b32_e32 v90, v123
	v_mov_b32_e32 v89, v123
	v_mov_b32_e32 v88, v123
	v_mov_b32_e32 v83, v123
	v_mov_b32_e32 v82, v123
	v_mov_b32_e32 v81, v123
	v_mov_b32_e32 v80, v123
	v_mov_b32_e32 v75, v123
	v_mov_b32_e32 v74, v123
	v_mov_b32_e32 v73, v123
	v_mov_b32_e32 v72, v123
	v_mov_b32_e32 v67, v123
	v_mov_b32_e32 v66, v123
	v_mov_b32_e32 v65, v123
	v_mov_b32_e32 v64, v123
	v_mov_b32_e32 v63, v123
	v_mov_b32_e32 v62, v123
	v_mov_b32_e32 v61, v123
	v_mov_b32_e32 v60, v123
	v_mov_b32_e32 v55, v123
	v_mov_b32_e32 v54, v123
	v_mov_b32_e32 v53, v123
	v_mov_b32_e32 v52, v123
	v_mov_b32_e32 v47, v123
	v_mov_b32_e32 v46, v123
	v_mov_b32_e32 v45, v123
	v_mov_b32_e32 v44, v123
	v_mov_b32_e32 v39, v123
	v_mov_b32_e32 v38, v123
	v_mov_b32_e32 v37, v123
	v_mov_b32_e32 v36, v123
	v_mov_b32_e32 v31, v123
	v_mov_b32_e32 v30, v123
	v_mov_b32_e32 v29, v123
	v_mov_b32_e32 v28, v123
	v_mov_b32_e32 v23, v123
	v_mov_b32_e32 v22, v123
	v_mov_b32_e32 v21, v123
	v_mov_b32_e32 v20, v123
	v_mov_b32_e32 v15, v123
	v_mov_b32_e32 v14, v123
	v_mov_b32_e32 v13, v123
	v_mov_b32_e32 v12, v123
	v_mov_b32_e32 v7, v123
	v_mov_b32_e32 v6, v123
	v_mov_b32_e32 v5, v123
	v_mov_b32_e32 v4, v123
	v_mov_b32_e32 v59, v123
	v_mov_b32_e32 v58, v123
	v_mov_b32_e32 v57, v123
	v_mov_b32_e32 v56, v123
	v_mov_b32_e32 v51, v123
	v_mov_b32_e32 v50, v123
	v_mov_b32_e32 v49, v123
	v_mov_b32_e32 v48, v123
	v_mov_b32_e32 v43, v123
	v_mov_b32_e32 v42, v123
	v_mov_b32_e32 v41, v123
	v_mov_b32_e32 v40, v123
	v_mov_b32_e32 v35, v123
	v_mov_b32_e32 v34, v123
	v_mov_b32_e32 v33, v123
	v_mov_b32_e32 v32, v123
	v_mov_b32_e32 v27, v123
	v_mov_b32_e32 v26, v123
	v_mov_b32_e32 v25, v123
	v_mov_b32_e32 v24, v123
	v_mov_b32_e32 v19, v123
	v_mov_b32_e32 v18, v123
	v_mov_b32_e32 v17, v123
	v_mov_b32_e32 v16, v123
	v_mov_b32_e32 v11, v123
	v_mov_b32_e32 v10, v123
	v_mov_b32_e32 v9, v123
	v_mov_b32_e32 v8, v123
	v_mov_b32_e32 v3, v123
	v_mov_b32_e32 v2, v123
	v_mov_b32_e32 v1, v123
	v_mov_b32_e32 v0, v123
	s_cbranch_vccnz .LBB0_951
	s_add_u32 s20, s20, 0x80
	s_addc_u32 s21, s21, 0
	s_add_u32 s2, s22, 0x100
	v_mov_b32_e32 v0, 0
	s_addc_u32 s3, s23, 0
	s_mov_b32 s0, 0
	v_mov_b32_e32 v1, v0
	v_mov_b32_e32 v2, v0
	v_mov_b32_e32 v3, v0
	v_mov_b32_e32 v8, v0
	v_mov_b32_e32 v9, v0
	v_mov_b32_e32 v10, v0
	v_mov_b32_e32 v11, v0
	v_mov_b32_e32 v16, v0
	v_mov_b32_e32 v17, v0
	v_mov_b32_e32 v18, v0
	v_mov_b32_e32 v19, v0
	v_mov_b32_e32 v24, v0
	v_mov_b32_e32 v25, v0
	v_mov_b32_e32 v26, v0
	v_mov_b32_e32 v27, v0
	v_mov_b32_e32 v32, v0
	v_mov_b32_e32 v33, v0
	v_mov_b32_e32 v34, v0
	v_mov_b32_e32 v35, v0
	v_mov_b32_e32 v40, v0
	v_mov_b32_e32 v41, v0
	v_mov_b32_e32 v42, v0
	v_mov_b32_e32 v43, v0
	v_mov_b32_e32 v48, v0
	v_mov_b32_e32 v49, v0
	v_mov_b32_e32 v50, v0
	v_mov_b32_e32 v51, v0
	v_mov_b32_e32 v56, v0
	v_mov_b32_e32 v57, v0
	v_mov_b32_e32 v58, v0
	v_mov_b32_e32 v59, v0
	v_mov_b32_e32 v4, v0
	v_mov_b32_e32 v5, v0
	v_mov_b32_e32 v6, v0
	v_mov_b32_e32 v7, v0
	v_mov_b32_e32 v12, v0
	v_mov_b32_e32 v13, v0
	v_mov_b32_e32 v14, v0
	v_mov_b32_e32 v15, v0
	v_mov_b32_e32 v20, v0
	v_mov_b32_e32 v21, v0
	v_mov_b32_e32 v22, v0
	v_mov_b32_e32 v23, v0
	v_mov_b32_e32 v28, v0
	v_mov_b32_e32 v29, v0
	v_mov_b32_e32 v30, v0
	v_mov_b32_e32 v31, v0
	v_mov_b32_e32 v36, v0
	v_mov_b32_e32 v37, v0
	v_mov_b32_e32 v38, v0
	v_mov_b32_e32 v39, v0
	v_mov_b32_e32 v44, v0
	v_mov_b32_e32 v45, v0
	v_mov_b32_e32 v46, v0
	v_mov_b32_e32 v47, v0
	v_mov_b32_e32 v52, v0
	v_mov_b32_e32 v53, v0
	v_mov_b32_e32 v54, v0
	v_mov_b32_e32 v55, v0
	v_mov_b32_e32 v60, v0
	v_mov_b32_e32 v61, v0
	v_mov_b32_e32 v62, v0
	v_mov_b32_e32 v63, v0
	v_mov_b32_e32 v64, v0
	v_mov_b32_e32 v65, v0
	v_mov_b32_e32 v66, v0
	v_mov_b32_e32 v67, v0
	v_mov_b32_e32 v72, v0
	v_mov_b32_e32 v73, v0
	v_mov_b32_e32 v74, v0
	v_mov_b32_e32 v75, v0
	v_mov_b32_e32 v80, v0
	v_mov_b32_e32 v81, v0
	v_mov_b32_e32 v82, v0
	v_mov_b32_e32 v83, v0
	v_mov_b32_e32 v88, v0
	v_mov_b32_e32 v89, v0
	v_mov_b32_e32 v90, v0
	v_mov_b32_e32 v91, v0
	v_mov_b32_e32 v96, v0
	v_mov_b32_e32 v97, v0
	v_mov_b32_e32 v98, v0
	v_mov_b32_e32 v99, v0
	v_mov_b32_e32 v104, v0
	v_mov_b32_e32 v105, v0
	v_mov_b32_e32 v106, v0
	v_mov_b32_e32 v107, v0
	v_mov_b32_e32 v112, v0
	v_mov_b32_e32 v113, v0
	v_mov_b32_e32 v114, v0
	v_mov_b32_e32 v115, v0
	v_mov_b32_e32 v124, v0
	v_mov_b32_e32 v125, v0
	v_mov_b32_e32 v126, v0
	v_mov_b32_e32 v127, v0
	v_mov_b32_e32 v68, v0
	v_mov_b32_e32 v69, v0
	v_mov_b32_e32 v70, v0
	v_mov_b32_e32 v71, v0
	v_mov_b32_e32 v76, v0
	v_mov_b32_e32 v77, v0
	v_mov_b32_e32 v78, v0
	v_mov_b32_e32 v79, v0
	v_mov_b32_e32 v84, v0
	v_mov_b32_e32 v85, v0
	v_mov_b32_e32 v86, v0
	v_mov_b32_e32 v87, v0
	v_mov_b32_e32 v92, v0
	v_mov_b32_e32 v93, v0
	v_mov_b32_e32 v94, v0
	v_mov_b32_e32 v95, v0
	v_mov_b32_e32 v100, v0
	v_mov_b32_e32 v101, v0
	v_mov_b32_e32 v102, v0
	v_mov_b32_e32 v103, v0
	v_mov_b32_e32 v108, v0
	v_mov_b32_e32 v109, v0
	v_mov_b32_e32 v110, v0
	v_mov_b32_e32 v111, v0
	v_mov_b32_e32 v116, v0
	v_mov_b32_e32 v117, v0
	v_mov_b32_e32 v118, v0
	v_mov_b32_e32 v119, v0
	v_mov_b32_e32 v120, v0
	v_mov_b32_e32 v121, v0
	v_mov_b32_e32 v122, v0
	v_mov_b32_e32 v123, v0
	.p2alignl 6, 3212836864

; template <class Epi>
; DEVI void gemm_phase(LAS unsigned char* lds, const Gemm g, const StaticOrder& S_, const Epi& E) {
;     ...
;     for (;;) {
;         const bool has_next = S_.next(ui + 1, nxt);
;         const char* nA = has_next ? (const char*)g.A + (size_t)nxt.pm * tstep : cA; const char* nB = has_next ? (const char*)g.Bt + (size_t)nxt.pn * tstep : cB;
;         for (int t = 0; t < nt; t += 2) {
;             const bool last = (t == nt - 2);
;             const char* a1 = cA + (size_t)(t + 1) * kstep;
;             const char* a2 = last ? nA : cA + (size_t)(t + 2) * kstep; const char* b2 = last ? nB : cB + (size_t)(t + 2) * kstep;
;     ...
; #pragma unroll
;         for (int a = 0; a < 2; ++a)
; #pragma unroll
;             for (int b = 0; b < 2; ++b)
; #pragma unroll
;                 for (int m = 0; m < 4; ++m)
; #pragma unroll
;                     for (int n = 0; n < 2; ++n) acc[a][b][m][n] = (f32x4){0.f, 0.f, 0.f, 0.f};
;         cur = nxt; cA = nA; cB = nB; ++ui;
.LBB0_989:
	v_mov_b32_e32 v127, 0
	s_andn2_b64 vcc, exec, s[18:19]
	v_mov_b32_e32 v126, v127
	v_mov_b32_e32 v125, v127
	v_mov_b32_e32 v124, v127
	v_mov_b32_e32 v123, v127
	v_mov_b32_e32 v122, v127
	v_mov_b32_e32 v121, v127
	v_mov_b32_e32 v120, v127
	v_mov_b32_e32 v111, v127
	v_mov_b32_e32 v110, v127
	v_mov_b32_e32 v109, v127
	v_mov_b32_e32 v108, v127
	v_mov_b32_e32 v107, v127
	v_mov_b32_e32 v106, v127
	v_mov_b32_e32 v105, v127
	v_mov_b32_e32 v104, v127
	v_mov_b32_e32 v95, v127
	v_mov_b32_e32 v94, v127
	v_mov_b32_e32 v93, v127
	v_mov_b32_e32 v92, v127
	v_mov_b32_e32 v91, v127
	v_mov_b32_e32 v90, v127
	v_mov_b32_e32 v89, v127
	v_mov_b32_e32 v88, v127
	v_mov_b32_e32 v79, v127
	v_mov_b32_e32 v78, v127
	v_mov_b32_e32 v77, v127
	v_mov_b32_e32 v76, v127
	v_mov_b32_e32 v75, v127
	v_mov_b32_e32 v74, v127
	v_mov_b32_e32 v73, v127
	v_mov_b32_e32 v72, v127
	v_mov_b32_e32 v119, v127
	v_mov_b32_e32 v118, v127
	v_mov_b32_e32 v117, v127
	v_mov_b32_e32 v116, v127
	v_mov_b32_e32 v115, v127
	v_mov_b32_e32 v114, v127
	v_mov_b32_e32 v113, v127
	v_mov_b32_e32 v112, v127
	v_mov_b32_e32 v103, v127
	v_mov_b32_e32 v102, v127
	v_mov_b32_e32 v101, v127
	v_mov_b32_e32 v100, v127
	v_mov_b32_e32 v99, v127
	v_mov_b32_e32 v98, v127
	v_mov_b32_e32 v97, v127
	v_mov_b32_e32 v96, v127
	v_mov_b32_e32 v87, v127
	v_mov_b32_e32 v86, v127
	v_mov_b32_e32 v85, v127
	v_mov_b32_e32 v84, v127
	v_mov_b32_e32 v83, v127
	v_mov_b32_e32 v82, v127
	v_mov_b32_e32 v81, v127
	v_mov_b32_e32 v80, v127
	v_mov_b32_e32 v71, v127
	v_mov_b32_e32 v70, v127
	v_mov_b32_e32 v69, v127
	v_mov_b32_e32 v68, v127
	v_mov_b32_e32 v67, v127
	v_mov_b32_e32 v66, v127
	v_mov_b32_e32 v65, v127
	v_mov_b32_e32 v64, v127
	v_mov_b32_e32 v63, v127
	v_mov_b32_e32 v62, v127
	v_mov_b32_e32 v61, v127
	v_mov_b32_e32 v60, v127
	v_mov_b32_e32 v59, v127
	v_mov_b32_e32 v58, v127
	v_mov_b32_e32 v57, v127
	v_mov_b32_e32 v56, v127
	v_mov_b32_e32 v47, v127
	v_mov_b32_e32 v46, v127
	v_mov_b32_e32 v45, v127
	v_mov_b32_e32 v44, v127
	v_mov_b32_e32 v43, v127
	v_mov_b32_e32 v42, v127
	v_mov_b32_e32 v41, v127
	v_mov_b32_e32 v40, v127
	v_mov_b32_e32 v31, v127
	v_mov_b32_e32 v30, v127
	v_mov_b32_e32 v29, v127
	v_mov_b32_e32 v28, v127
	v_mov_b32_e32 v27, v127
	v_mov_b32_e32 v26, v127
	v_mov_b32_e32 v25, v127
	v_mov_b32_e32 v24, v127
	v_mov_b32_e32 v15, v127
	v_mov_b32_e32 v14, v127
	v_mov_b32_e32 v13, v127
	v_mov_b32_e32 v12, v127
	v_mov_b32_e32 v11, v127
	v_mov_b32_e32 v10, v127
	v_mov_b32_e32 v9, v127
	v_mov_b32_e32 v8, v127
	v_mov_b32_e32 v55, v127
	v_mov_b32_e32 v54, v127
	v_mov_b32_e32 v53, v127
	v_mov_b32_e32 v52, v127
	v_mov_b32_e32 v51, v127
	v_mov_b32_e32 v50, v127
	v_mov_b32_e32 v49, v127
	v_mov_b32_e32 v48, v127
	v_mov_b32_e32 v39, v127
	v_mov_b32_e32 v38, v127
	v_mov_b32_e32 v37, v127
	v_mov_b32_e32 v36, v127
	v_mov_b32_e32 v35, v127
	v_mov_b32_e32 v34, v127
	v_mov_b32_e32 v33, v127
	v_mov_b32_e32 v32, v127
	v_mov_b32_e32 v23, v127
	v_mov_b32_e32 v22, v127
	v_mov_b32_e32 v21, v127
	v_mov_b32_e32 v20, v127
	v_mov_b32_e32 v19, v127
	v_mov_b32_e32 v18, v127
	v_mov_b32_e32 v17, v127
	v_mov_b32_e32 v16, v127
	v_mov_b32_e32 v7, v127
	v_mov_b32_e32 v6, v127
	v_mov_b32_e32 v5, v127
	v_mov_b32_e32 v4, v127
	v_mov_b32_e32 v3, v127
	v_mov_b32_e32 v2, v127
	v_mov_b32_e32 v1, v127
	v_mov_b32_e32 v0, v127
	s_cbranch_vccnz .LBB0_978
	s_add_u32 s20, s20, 0x80
	s_addc_u32 s21, s21, 0
	s_add_u32 s2, s22, 0x100
	v_mov_b32_e32 v0, 0
	s_addc_u32 s3, s23, 0
	s_mov_b32 s0, 0
	v_mov_b32_e32 v1, v0
	v_mov_b32_e32 v2, v0
	v_mov_b32_e32 v3, v0
	v_mov_b32_e32 v4, v0
	v_mov_b32_e32 v5, v0
	v_mov_b32_e32 v6, v0
	v_mov_b32_e32 v7, v0
	v_mov_b32_e32 v16, v0
	v_mov_b32_e32 v17, v0
	v_mov_b32_e32 v18, v0
	v_mov_b32_e32 v19, v0
	v_mov_b32_e32 v20, v0
	v_mov_b32_e32 v21, v0
	v_mov_b32_e32 v22, v0
	v_mov_b32_e32 v23, v0
	v_mov_b32_e32 v32, v0
	v_mov_b32_e32 v33, v0
	v_mov_b32_e32 v34, v0
	v_mov_b32_e32 v35, v0
	v_mov_b32_e32 v36, v0
	v_mov_b32_e32 v37, v0
	v_mov_b32_e32 v38, v0
	v_mov_b32_e32 v39, v0
	v_mov_b32_e32 v48, v0
	v_mov_b32_e32 v49, v0
	v_mov_b32_e32 v50, v0
	v_mov_b32_e32 v51, v0
	v_mov_b32_e32 v52, v0
	v_mov_b32_e32 v53, v0
	v_mov_b32_e32 v54, v0
	v_mov_b32_e32 v55, v0
	v_mov_b32_e32 v8, v0
	v_mov_b32_e32 v9, v0
	v_mov_b32_e32 v10, v0
	v_mov_b32_e32 v11, v0
	v_mov_b32_e32 v12, v0
	v_mov_b32_e32 v13, v0
	v_mov_b32_e32 v14, v0
	v_mov_b32_e32 v15, v0
	v_mov_b32_e32 v24, v0
	v_mov_b32_e32 v25, v0
	v_mov_b32_e32 v26, v0
	v_mov_b32_e32 v27, v0
	v_mov_b32_e32 v28, v0
	v_mov_b32_e32 v29, v0
	v_mov_b32_e32 v30, v0
	v_mov_b32_e32 v31, v0
	v_mov_b32_e32 v40, v0
	v_mov_b32_e32 v41, v0
	v_mov_b32_e32 v42, v0
	v_mov_b32_e32 v43, v0
	v_mov_b32_e32 v44, v0
	v_mov_b32_e32 v45, v0
	v_mov_b32_e32 v46, v0
	v_mov_b32_e32 v47, v0
	v_mov_b32_e32 v56, v0
	v_mov_b32_e32 v57, v0
	v_mov_b32_e32 v58, v0
	v_mov_b32_e32 v59, v0
	v_mov_b32_e32 v60, v0
	v_mov_b32_e32 v61, v0
	v_mov_b32_e32 v62, v0
	v_mov_b32_e32 v63, v0
	v_mov_b32_e32 v64, v0
	v_mov_b32_e32 v65, v0
	v_mov_b32_e32 v66, v0
	v_mov_b32_e32 v67, v0
	v_mov_b32_e32 v68, v0
	v_mov_b32_e32 v69, v0
	v_mov_b32_e32 v70, v0
	v_mov_b32_e32 v71, v0
	v_mov_b32_e32 v80, v0
	v_mov_b32_e32 v81, v0
	v_mov_b32_e32 v82, v0
	v_mov_b32_e32 v83, v0
	v_mov_b32_e32 v84, v0
	v_mov_b32_e32 v85, v0
	v_mov_b32_e32 v86, v0
	v_mov_b32_e32 v87, v0
	v_mov_b32_e32 v96, v0
	v_mov_b32_e32 v97, v0
	v_mov_b32_e32 v98, v0
	v_mov_b32_e32 v99, v0
	v_mov_b32_e32 v100, v0
	v_mov_b32_e32 v101, v0
	v_mov_b32_e32 v102, v0
	v_mov_b32_e32 v103, v0
	v_mov_b32_e32 v112, v0
	v_mov_b32_e32 v113, v0
	v_mov_b32_e32 v114, v0
	v_mov_b32_e32 v115, v0
	v_mov_b32_e32 v116, v0
	v_mov_b32_e32 v117, v0
	v_mov_b32_e32 v118, v0
	v_mov_b32_e32 v119, v0
	v_mov_b32_e32 v72, v0
	v_mov_b32_e32 v73, v0
	v_mov_b32_e32 v74, v0
	v_mov_b32_e32 v75, v0
	v_mov_b32_e32 v76, v0
	v_mov_b32_e32 v77, v0
	v_mov_b32_e32 v78, v0
	v_mov_b32_e32 v79, v0
	v_mov_b32_e32 v88, v0
	v_mov_b32_e32 v89, v0
	v_mov_b32_e32 v90, v0
	v_mov_b32_e32 v91, v0
	v_mov_b32_e32 v92, v0
	v_mov_b32_e32 v93, v0
	v_mov_b32_e32 v94, v0
	v_mov_b32_e32 v95, v0
	v_mov_b32_e32 v104, v0
	v_mov_b32_e32 v105, v0
	v_mov_b32_e32 v106, v0
	v_mov_b32_e32 v107, v0
	v_mov_b32_e32 v108, v0
	v_mov_b32_e32 v109, v0
	v_mov_b32_e32 v110, v0
	v_mov_b32_e32 v111, v0
	v_mov_b32_e32 v120, v0
	v_mov_b32_e32 v121, v0
	v_mov_b32_e32 v122, v0
	v_mov_b32_e32 v123, v0
	v_mov_b32_e32 v124, v0
	v_mov_b32_e32 v125, v0
	v_mov_b32_e32 v126, v0
	v_mov_b32_e32 v127, v0
	.p2alignl 6, 3212836864
